# fox_prompt loop: Q-fragment loads retired before the loop so the QK block no longer waits (vmcnt 1/0) on its own next-tile K/V prefetch; passC tile staging loads pipelined
# speedup vs baseline: 1.0081x; 1.0081x over previous
; #define GAS __attribute__((address_space(1)))
; #define AT_LOAD(t) do { _Pragma("unroll") for (int i_ = 0; i_ < 2; ++i_) { const int c_ = tid + 512 * i_, row_ = c_ >> 4, ch_ = c_ & 15; \
;         kr[i_] = *(const GAS u32x4*)(Kg + (size_t)(64 * (t) + row_) * NP + ch_ * 8); vr[i_] = *(const GAS u32x4*)(Vg + (size_t)(64 * (t) + row_) * NP + ch_ * 8); } } while (0)
; #define AT_STORE(buf) do { _Pragma("unroll") for (int i_ = 0; i_ < 2; ++i_) { const int c_ = tid + 512 * i_, row_ = c_ >> 4, ch_ = c_ & 15; \
;         *(LAS u32x4*)(L + AT_K + (buf) * 17408 + row_ * 272 + ch_ * 16) = kr[i_]; *(LAS u32x4*)(L + AT_V + (buf) * 20480 + row_ * AVP + ch_ * 16) = vr[i_]; } } while (0)
; __device__ __forceinline__ void fox_prompt_unit(LAS char* L, const bf16_t* P, const float* lfT, bf16_t* MIX, int b, int h, int qb, const int wv) {
;     ...
;     const bf16_t* Kg = P + rowb * NP + PC_KB + h * 128; const bf16_t* Vg = P + rowb * NP + PC_VB + h * 128;
;     u32x4 kr[2], vr[2];
;     ...
;     bf16x8 qf[8];
;     { const bf16_t* Qg = P + (rowb + 256 * qb + 32 * wid + r32) * NP + PC_QB + h * 128 + 8 * hi;
; #pragma unroll
;         for (int kk = 0; kk < 8; ++kk) qf[kk] = *(const GAS bf16x8*)(Qg + 16 * kk); }
;     f32x16 o[4];
; #pragma unroll
;     for (int d = 0; d < 4; ++d)
; #pragma unroll
;         for (int r = 0; r < 16; ++r) o[d][r] = 0.f;
;     float m = -INFINITY, l = 0.f;
;     AT_LOAD(0); AT_STORE(0);
;     __syncthreads();
.LBB0_196:
	s_or_b64 exec, exec, s[0:1]
	s_lshl_b32 s7, s7, 2
	s_lshl_b32 s0, s6, 12
	s_mul_i32 s6, s6, 0x3000000
	s_add_u32 s1, s20, s6
	s_addc_u32 s14, s21, 0
	s_lshl_b32 s8, s15, 8
	s_sub_i32 s0, s0, s8
	s_lshl_b32 s9, s9, 5
	s_lshl_b32 s6, s2, 7
	s_addk_i32 s0, 0xf00
	s_ashr_i32 s16, s9, 31
	s_add_u32 s17, s9, s0
	s_addc_u32 s16, s16, 0
	s_lshl_b32 s2, s2, 8
	s_add_u32 s0, s1, s2
	v_and_b32_e32 v2, 0x78, v10
	s_addc_u32 s1, s14, 0
	v_lshlrev_b32_e32 v2, 1, v2
	v_mov_b32_e32 v3, v1
	v_lshl_add_u64 v[2:3], s[0:1], 0, v[2:3]
	s_mov_b64 s[0:1], 0x2000
	v_lshl_add_u64 v[154:155], v[2:3], 0, s[0:1]
	s_mov_b64 s[0:1], 0x2800
	v_ashrrev_i32_e32 v6, 4, v0
	v_add_u32_e32 v0, 0x200, v0
	v_lshl_add_u64 v[156:157], v[2:3], 0, s[0:1]
	v_mad_i64_i32 v[2:3], s[0:1], v6, s63, v[154:155]
	v_ashrrev_i32_e32 v7, 4, v0
	v_mad_i64_i32 v[4:5], s[0:1], v6, s63, v[156:157]
	global_load_dwordx4 v[98:101], v[2:3], off
	global_load_dwordx4 v[102:105], v[4:5], off
	v_mad_i64_i32 v[2:3], s[0:1], v7, s63, v[154:155]
	v_and_b32_e32 v9, 31, v14
	v_mad_i64_i32 v[4:5], s[0:1], v7, s63, v[156:157]
	global_load_dwordx4 v[106:109], v[2:3], off
	global_load_dwordx4 v[110:113], v[4:5], off
	v_or_b32_e32 v152, s17, v9
	v_mov_b64_e32 v[2:3], s[20:21]
	v_mad_u64_u32 v[2:3], s[0:1], v152, s63, v[2:3]
	v_mov_b32_e32 v0, 0x3000
	v_lshrrev_b32_e32 v8, 5, v8
	v_mad_i32_i24 v3, s16, v0, v3
	v_lshl_add_u64 v[2:3], v[2:3], 0, s[2:3]
	v_lshlrev_b32_e32 v0, 4, v8
	v_lshl_add_u64 v[2:3], v[2:3], 0, v[0:1]
	s_mov_b64 s[0:1], 0x1800
	v_lshl_add_u64 v[4:5], v[2:3], 0, s[0:1]
	v_add_co_u32_e32 v2, vcc, s60, v2
	v_lshlrev_b32_e32 v164, 2, v8
	s_nop 0
	v_addc_co_u32_e32 v3, vcc, 0, v3, vcc
	global_load_dwordx4 v[114:117], v[4:5], off offset:32
	global_load_dwordx4 v[118:121], v[4:5], off offset:64
	global_load_dwordx4 v[122:125], v[4:5], off offset:96
	global_load_dwordx4 v[126:129], v[4:5], off offset:128
	global_load_dwordx4 v[130:133], v[4:5], off offset:160
	global_load_dwordx4 v[134:137], v[4:5], off offset:192
	global_load_dwordx4 v[138:141], v[2:3], off offset:2048
	global_load_dwordx4 v[142:145], v[4:5], off offset:224
	v_lshlrev_b32_e32 v3, 4, v14
	v_and_b32_e32 v2, 16, v14
	v_lshrrev_b32_e32 v4, 2, v14
	v_lshlrev_b32_e32 v5, 2, v14
	v_and_b32_e32 v3, 0xf0, v3
	v_mul_lo_u32 v165, v6, s56
	v_mul_lo_u32 v166, v6, s18
	v_mul_u32_u24_e32 v8, 0x110, v9
	v_and_or_b32 v2, v5, 12, v2
	v_add_u32_e32 v167, 0, v3
	v_mul_lo_u32 v168, v7, s56
	v_mul_lo_u32 v169, v7, s18
	v_and_or_b32 v3, v4, 3, v164
	v_lshlrev_b32_e32 v2, 1, v2
	v_add3_u32 v170, 0, v8, v0
	v_add_u32_e32 v4, v167, v165
	v_add_u32_e32 v5, v167, v166
	v_add_u32_e32 v8, v167, v168
	v_add_u32_e32 v10, v167, v169
	v_mul_u32_u24_e32 v3, 0x140, v3
	s_add_i32 s0, 0, 0x12800
	v_mov_b32_e32 v14, v1
	v_mov_b32_e32 v15, v1
	v_or_b32_e32 v171, s9, v9
	v_add3_u32 v172, 0, v3, v2
	v_add_u32_e32 v173, s0, v0
	v_add_u32_e32 v175, 64, v7
	v_add_u32_e32 v176, 64, v6
	v_mov_b32_e32 v0, v1
	v_mov_b32_e32 v2, v1
	v_mov_b32_e32 v3, v1
	v_mov_b32_e32 v6, v1
	v_mov_b32_e32 v7, v1
	v_mov_b32_e32 v9, v1
	v_mov_b32_e32 v11, v1
	v_mov_b32_e32 v12, v1
	v_mov_b32_e32 v13, v1
	s_waitcnt vmcnt(11)
	ds_write_b128 v4, v[98:101]
	s_waitcnt vmcnt(10)
	ds_write_b128 v5, v[102:105] offset:34816
	s_waitcnt vmcnt(9)
	ds_write_b128 v8, v[106:109]
	s_waitcnt vmcnt(8)
	ds_write_b128 v10, v[110:113] offset:34816
	v_mov_b32_e32 v4, v1
	v_mov_b32_e32 v5, v1
	v_mov_b32_e32 v8, v1
	v_mov_b32_e32 v10, v1
	v_mov_b64_e32 v[64:65], v[14:15]
	v_mov_b64_e32 v[48:49], v[14:15]
	v_mov_b64_e32 v[32:33], v[14:15]
	s_lshl_b32 s0, s15, 2
	v_mov_b64_e32 v[62:63], v[12:13]
	v_mov_b64_e32 v[60:61], v[10:11]
	v_mov_b64_e32 v[58:59], v[8:9]
	v_mov_b64_e32 v[56:57], v[6:7]
	v_mov_b64_e32 v[54:55], v[4:5]
	v_mov_b64_e32 v[52:53], v[2:3]
	v_mov_b64_e32 v[50:51], v[0:1]
	v_mov_b64_e32 v[46:47], v[12:13]
	v_mov_b64_e32 v[44:45], v[10:11]
	v_mov_b64_e32 v[42:43], v[8:9]
	v_mov_b64_e32 v[40:41], v[6:7]
	v_mov_b64_e32 v[38:39], v[4:5]
	v_mov_b64_e32 v[36:37], v[2:3]
	v_mov_b64_e32 v[34:35], v[0:1]
	v_mov_b64_e32 v[30:31], v[12:13]
	v_mov_b64_e32 v[28:29], v[10:11]
	v_mov_b64_e32 v[26:27], v[8:9]
	v_mov_b64_e32 v[24:25], v[6:7]
	v_mov_b64_e32 v[22:23], v[4:5]
	v_mov_b64_e32 v[20:21], v[2:3]
	v_mov_b64_e32 v[18:19], v[0:1]
	v_mov_b64_e32 v[16:17], v[14:15]
	s_mov_b32 s2, 0
	v_mov_b32_e32 v153, s16
	s_or_b32 s14, s9, 31
	v_or_b32_e32 v174, s8, v164
	s_sub_i32 s15, s0, 64
	v_mov_b32_e32 v177, 0
	v_mov_b32_e32 v158, 0xff800000
	v_mov_b64_e32 v[14:15], v[12:13]
	v_mov_b64_e32 v[12:13], v[10:11]
	v_mov_b64_e32 v[10:11], v[8:9]
	v_mov_b64_e32 v[8:9], v[6:7]
	v_mov_b64_e32 v[6:7], v[4:5]
	v_mov_b64_e32 v[4:5], v[2:3]
	v_mov_b64_e32 v[2:3], v[0:1]
	s_mov_b32 s17, 0
	s_waitcnt vmcnt(0) lgkmcnt(0)
	s_barrier

; #define LAS __attribute__((address_space(3)))
; __device__ __forceinline__ int crow(int r, int hi) { return (r & 3) + 8 * (r >> 2) + 4 * hi; }
; __device__ __forceinline__ f32x16 mfma32(bf16x8 a, bf16x8 b, f32x16 c) { return __builtin_amdgcn_mfma_f32_32x32x16_bf16(a, b, c, 0, 0, 0); }
; __device__ __forceinline__ void fox_prompt_unit(LAS char* L, const bf16_t* P, const float* lfT, bf16_t* MIX, int b, int h, int qb, const int wv) {
;     ...
;         const int jb = t - (NT - 4);
;         if (!(jb >= 0 && 64 * jb > 32 * wid + 31)) {
;             LAS const char* Kb = L + AT_K + (t & 1) * 17408; LAS const char* Vb = L + AT_V + (t & 1) * 20480;
;             LAS const float* nf = nfk + 64 * t;
;             f32x16 s0, s1;
; #pragma unroll
;             for (int g = 0; g < 4; ++g) { const f32x4 a = *(LAS const f32x4*)(nf + 8 * g + 4 * hi), c = *(LAS const f32x4*)(nf + 32 + 8 * g + 4 * hi);
;                 s0[4 * g] = a[0]; s0[4 * g + 1] = a[1]; s0[4 * g + 2] = a[2]; s0[4 * g + 3] = a[3]; s1[4 * g] = c[0]; s1[4 * g + 1] = c[1]; s1[4 * g + 2] = c[2]; s1[4 * g + 3] = c[3]; }
;             {
;                 bf16x8 ka[16];
; #pragma unroll
;                 for (int kk = 0; kk < 8; ++kk) { ka[2 * kk] = *(LAS const bf16x8*)(Kb + r32 * 272 + kk * 32 + hi * 16); ka[2 * kk + 1] = *(LAS const bf16x8*)(Kb + (32 + r32) * 272 + kk * 32 + hi * 16); }
;                 __builtin_amdgcn_sched_barrier(0);
; #pragma unroll
;                 for (int kk = 0; kk < 8; ++kk) { s0 = mfma32(ka[2 * kk], qf[kk], s0); s1 = mfma32(ka[2 * kk + 1], qf[kk], s1); }
;                 __builtin_amdgcn_sched_barrier(0);
;             }
;             if (jb >= 0 && 64 * jb + 63 > 32 * wid) { const int q = 32 * wid + r32;
; #pragma unroll
;                 for (int r = 0; r < 16; ++r) { const int kv = 64 * jb + crow(r, hi); if (kv > q) s0[r] = -INFINITY; if (kv + 32 > q) s1[r] = -INFINITY; } }
.LBB0_199:
	s_add_i32 s22, s15, s17
	s_cmp_gt_i32 s22, -5
	s_cselect_b64 s[38:39], -1, 0
	s_add_i32 s22, s8, s2
	s_add_i32 s23, s22, 0xfffff100
	s_cmp_gt_i32 s23, s14
	s_cselect_b64 s[34:35], -1, 0
	s_and_b64 s[34:35], s[38:39], s[34:35]
	s_and_b64 vcc, exec, s[34:35]
	s_cbranch_vccnz .LBB0_203
	s_and_b32 s17, s17, 1
	s_mul_i32 s23, s17, 0x4400
	v_add_u32_e32 v0, s23, v170
	ds_read_b128 v[82:85], v173
	ds_read_b128 v[86:89], v173 offset:32
	ds_read_b128 v[66:69], v173 offset:128
	ds_read_b128 v[70:73], v173 offset:160
	ds_read_b128 v[90:93], v173 offset:64
	ds_read_b128 v[94:97], v173 offset:96
	ds_read_b128 v[74:77], v173 offset:192
	ds_read_b128 v[78:81], v173 offset:224
	ds_read_b128 v[160:163], v0
	ds_read_b128 v[190:193], v0 offset:32
	ds_read_b128 v[194:197], v0 offset:8704
	ds_read_b128 v[198:201], v0 offset:8736
	ds_read_b128 v[202:205], v0 offset:64
	ds_read_b128 v[206:209], v0 offset:96
	ds_read_b128 v[210:213], v0 offset:8768
	ds_read_b128 v[214:217], v0 offset:8800
	ds_read_b128 v[218:221], v0 offset:128
	ds_read_b128 v[222:225], v0 offset:160
	ds_read_b128 v[226:229], v0 offset:8832
	ds_read_b128 v[230:233], v0 offset:8864
	ds_read_b128 v[234:237], v0 offset:192
	ds_read_b128 v[238:241], v0 offset:224
	ds_read_b128 v[242:245], v0 offset:8896
	ds_read_b128 v[246:249], v0 offset:8928
	s_waitcnt lgkmcnt(14)
	v_mfma_f32_32x32x16_bf16 v[82:97], v[160:163], v[138:141], v[82:97]
	s_waitcnt lgkmcnt(13)
	v_mfma_f32_32x32x16_bf16 v[66:81], v[194:197], v[138:141], v[66:81]
	v_mfma_f32_32x32x16_bf16 v[82:97], v[190:193], v[114:117], v[82:97]
	s_waitcnt lgkmcnt(12)
	v_mfma_f32_32x32x16_bf16 v[66:81], v[198:201], v[114:117], v[66:81]
	s_waitcnt lgkmcnt(11)
	v_mfma_f32_32x32x16_bf16 v[82:97], v[202:205], v[118:121], v[82:97]
	s_waitcnt lgkmcnt(9)
	v_mfma_f32_32x32x16_bf16 v[66:81], v[210:213], v[118:121], v[66:81]
	v_mfma_f32_32x32x16_bf16 v[82:97], v[206:209], v[122:125], v[82:97]
	s_waitcnt lgkmcnt(8)
	v_mfma_f32_32x32x16_bf16 v[66:81], v[214:217], v[122:125], v[66:81]
	s_waitcnt lgkmcnt(7)
	v_mfma_f32_32x32x16_bf16 v[82:97], v[218:221], v[126:129], v[82:97]
	s_waitcnt lgkmcnt(5)
	v_mfma_f32_32x32x16_bf16 v[66:81], v[226:229], v[126:129], v[66:81]
	v_mfma_f32_32x32x16_bf16 v[82:97], v[222:225], v[130:133], v[82:97]
	s_waitcnt lgkmcnt(4)
	v_mfma_f32_32x32x16_bf16 v[66:81], v[230:233], v[130:133], v[66:81]
	s_waitcnt lgkmcnt(3)
	v_mfma_f32_32x32x16_bf16 v[82:97], v[234:237], v[134:137], v[82:97]
	s_waitcnt lgkmcnt(1)
	v_mfma_f32_32x32x16_bf16 v[66:81], v[242:245], v[134:137], v[66:81]
	v_mfma_f32_32x32x16_bf16 v[82:97], v[238:241], v[142:145], v[82:97]
	s_waitcnt lgkmcnt(0)
	v_mfma_f32_32x32x16_bf16 v[66:81], v[246:249], v[142:145], v[66:81]
	s_addk_i32 s22, 0xf13f
	s_cmp_gt_i32 s22, s9
	s_cselect_b64 s[22:23], -1, 0
	s_and_b64 s[22:23], s[38:39], s[22:23]
	s_andn2_b64 vcc, exec, s[22:23]
	s_cbranch_vccnz .LBB0_202
	v_add_u32_e32 v0, s2, v174
	v_add_u32_e32 v147, 0xfffff120, v0
	v_add_u32_e32 v146, 0xfffff100, v0
	v_cmp_le_i32_e32 vcc, v147, v171
	s_nop 1
	v_cndmask_b32_e32 v66, v186, v66, vcc
	v_cmp_lt_i32_e32 vcc, v146, v171
	s_nop 1
	v_cndmask_b32_e32 v83, v186, v83, vcc
	v_cmp_le_i32_e32 vcc, v146, v171
	v_add_u32_e32 v146, 0xfffff121, v0
	s_nop 0
	v_cndmask_b32_e32 v82, v186, v82, vcc
	v_cmp_le_i32_e32 vcc, v146, v171
	v_add_u32_e32 v146, 0xfffff102, v0
	s_nop 0
	v_cndmask_b32_e32 v67, v186, v67, vcc
	v_cmp_le_i32_e32 vcc, v146, v171
	v_add_u32_e32 v146, 0xfffff122, v0
	s_nop 0
	v_cndmask_b32_e32 v84, v186, v84, vcc
	v_cmp_le_i32_e32 vcc, v146, v171
	v_add_u32_e32 v146, 0xfffff103, v0
	s_nop 0
	v_cndmask_b32_e32 v68, v186, v68, vcc
	v_cmp_le_i32_e32 vcc, v146, v171
	v_add_u32_e32 v146, 0xfffff123, v0
	s_nop 0
	v_cndmask_b32_e32 v85, v186, v85, vcc
	v_cmp_le_i32_e32 vcc, v146, v171
	v_add_u32_e32 v146, 0xfffff108, v0
	s_nop 0
	v_cndmask_b32_e32 v69, v186, v69, vcc
	v_cmp_le_i32_e32 vcc, v146, v171
	v_add_u32_e32 v146, 0xfffff128, v0
	s_nop 0
	v_cndmask_b32_e32 v86, v186, v86, vcc
	v_cmp_le_i32_e32 vcc, v146, v171
	v_add_u32_e32 v146, 0xfffff109, v0
	s_nop 0
	v_cndmask_b32_e32 v70, v186, v70, vcc
	v_cmp_le_i32_e32 vcc, v146, v171
	v_add_u32_e32 v146, 0xfffff129, v0
	s_nop 0
	v_cndmask_b32_e32 v87, v186, v87, vcc
	v_cmp_le_i32_e32 vcc, v146, v171
	v_add_u32_e32 v146, 0xfffff10a, v0
	s_nop 0
	v_cndmask_b32_e32 v71, v186, v71, vcc
	v_cmp_le_i32_e32 vcc, v146, v171
	v_add_u32_e32 v146, 0xfffff12a, v0
	s_nop 0
	v_cndmask_b32_e32 v88, v186, v88, vcc
	v_cmp_le_i32_e32 vcc, v146, v171
	v_add_u32_e32 v146, 0xfffff10b, v0
	s_nop 0
	v_cndmask_b32_e32 v72, v186, v72, vcc
	v_cmp_le_i32_e32 vcc, v146, v171
	v_add_u32_e32 v146, 0xfffff12b, v0
	s_nop 0
	v_cndmask_b32_e32 v89, v186, v89, vcc
	v_cmp_le_i32_e32 vcc, v146, v171
	v_add_u32_e32 v146, 0xfffff110, v0
	s_nop 0
	v_cndmask_b32_e32 v73, v186, v73, vcc
	v_cmp_le_i32_e32 vcc, v146, v171
	v_add_u32_e32 v146, 0xfffff130, v0
	s_nop 0
	v_cndmask_b32_e32 v90, v186, v90, vcc
	v_cmp_le_i32_e32 vcc, v146, v171
	v_add_u32_e32 v146, 0xfffff111, v0
	s_nop 0
	v_cndmask_b32_e32 v74, v186, v74, vcc
	v_cmp_le_i32_e32 vcc, v146, v171
	v_add_u32_e32 v146, 0xfffff131, v0
	s_nop 0
	v_cndmask_b32_e32 v91, v186, v91, vcc
	v_cmp_le_i32_e32 vcc, v146, v171
	v_add_u32_e32 v146, 0xfffff112, v0
	s_nop 0
	v_cndmask_b32_e32 v75, v186, v75, vcc
	v_cmp_le_i32_e32 vcc, v146, v171
	v_add_u32_e32 v146, 0xfffff132, v0
	s_nop 0
	v_cndmask_b32_e32 v92, v186, v92, vcc
	v_cmp_le_i32_e32 vcc, v146, v171
	v_add_u32_e32 v146, 0xfffff113, v0
	s_nop 0
	v_cndmask_b32_e32 v76, v186, v76, vcc
	v_cmp_le_i32_e32 vcc, v146, v171
	v_add_u32_e32 v146, 0xfffff133, v0
	s_nop 0
	v_cndmask_b32_e32 v93, v186, v93, vcc
	v_cmp_le_i32_e32 vcc, v146, v171
	v_add_u32_e32 v146, 0xfffff118, v0
	s_nop 0
	v_cndmask_b32_e32 v77, v186, v77, vcc
	v_cmp_le_i32_e32 vcc, v146, v171
	v_add_u32_e32 v146, 0xfffff138, v0
	s_nop 0
	v_cndmask_b32_e32 v94, v186, v94, vcc
	v_cmp_le_i32_e32 vcc, v146, v171
	v_add_u32_e32 v146, 0xfffff119, v0
	s_nop 0
	v_cndmask_b32_e32 v78, v186, v78, vcc
	v_cmp_le_i32_e32 vcc, v146, v171
	v_add_u32_e32 v146, 0xfffff139, v0
	s_nop 0
	v_cndmask_b32_e32 v95, v186, v95, vcc
	v_cmp_le_i32_e32 vcc, v146, v171
	v_add_u32_e32 v146, 0xfffff11a, v0
	s_nop 0
	v_cndmask_b32_e32 v79, v186, v79, vcc
	v_cmp_le_i32_e32 vcc, v146, v171
	v_add_u32_e32 v146, 0xfffff13a, v0
	s_nop 0
	v_cndmask_b32_e32 v96, v186, v96, vcc
	v_cmp_le_i32_e32 vcc, v146, v171
	v_add_u32_e32 v146, 0xfffff11b, v0
	v_add_u32_e32 v0, 0xfffff13b, v0
	v_cndmask_b32_e32 v80, v186, v80, vcc
	v_cmp_le_i32_e32 vcc, v146, v171
	s_nop 1
	v_cndmask_b32_e32 v97, v186, v97, vcc
	v_cmp_le_i32_e32 vcc, v0, v171
	s_nop 1
	v_cndmask_b32_e32 v81, v186, v81, vcc

; #define LAS __attribute__((address_space(3)))
; #define GAS __attribute__((address_space(1)))
; __device__ __forceinline__ unsigned pkbf(float lo, float hi) { f32x2 v = {lo, hi}; bf16x2_t b = __builtin_convertvector(v, bf16x2_t); return __builtin_bit_cast(unsigned, b); }
; __device__ __forceinline__ f32x4 mfma16(bf16x8 a, bf16x8 b, f32x4 c) { return __builtin_amdgcn_mfma_f32_16x16x32_bf16(a, b, c, 0, 0, 0); }
; __device__ __forceinline__ void mlstm_passC(LAS char* L, const bf16_t* P, const float* G, const bf16_t* UC, const float* GS, const float* NSV, const float* MSV, bf16_t* MIX, const float* ghead,
;                                             int ci, int j, size_t rb, int hh, const int wv) {
;     ...
;     for (int i = 0; i < 2; ++i) { const int c = tid + 512 * i, row = c >> 4, ch = c & 15;
;         *(LAS u32x4*)(L + ML_Q + row * 272 + ch * 16) = *(const GAS u32x4*)(P + (rb + row) * NP + PC_QA + hh * 128 + ch * 8);
;         *(LAS u32x4*)(L + ML_K + row * 272 + ch * 16) = *(const GAS u32x4*)(P + (rb + row) * NP + PC_KA + hh * 128 + ch * 8); }
; #pragma unroll
;     for (int i = 0; i < 4; ++i) { const int c = tid + 512 * i, row = c >> 5, ch = c & 31;
;         *(LAS u32x4*)(L + ML_V + row * VP + ch * 16) = *(const GAS u32x4*)(P + (rb + row) * NP + PC_VA + hh * 256 + ch * 8); }
;     __syncthreads();
;     {
;         const int fr = lane & 15, fq = lane >> 4;
; #pragma unroll
;         for (int bi = 0; bi < 2; ++bi) { const int id = 2 * wid + bi, sb = id >> 2, tb = id & 3; const int t = 16 * tb + fr, s0 = 16 * sb + 4 * fq;
;             u32x2 ow = (u32x2){0u, 0u};
;             if (sb <= tb) { f32x4 acc = (f32x4){0.f, 0.f, 0.f, 0.f};
; #pragma unroll
;                 for (int kk = 0; kk < 4; ++kk) { const bf16x8 a = *(LAS const bf16x8*)(L + ML_K + (16 * sb + fr) * 272 + kk * 64 + fq * 16), q = *(LAS const bf16x8*)(L + ML_Q + (16 * tb + fr) * 272 + kk * 64 + fq * 16);
;                     acc = mfma16(a, q, acc); }
;                 const float rt = ROWT[t]; const f32x4 cs = *(LAS const f32x4*)(COLS + s0); float v[4];
; #pragma unroll
;                 for (int i = 0; i < 4; ++i) v[i] = (s0 + i <= t) ? acc[i] * __expf(rt + cs[i]) : 0.f;
;                 ow.x = pkbf(v[0], v[1]); ow.y = pkbf(v[2], v[3]); }
.LBB0_887:
	s_or_b64 exec, exec, s[0:1]
	v_ashrrev_i32_e32 v18, 4, v6
	v_ashrrev_i32_e32 v19, 31, v18
	v_lshl_add_u64 v[10:11], s[46:47], 0, v[18:19]
	v_mov_b64_e32 v[20:21], s[20:21]
	v_mad_u64_u32 v[12:13], s[0:1], v10, s63, v[20:21]
	v_mov_b32_e32 v10, v13
	v_mad_u64_u32 v[10:11], s[0:1], v11, s63, v[10:11]
	v_and_b32_e32 v9, 15, v8
	v_mov_b32_e32 v13, v10
	v_lshlrev_b32_e32 v14, 4, v9
	v_lshl_add_u64 v[10:11], v[12:13], 0, s[2:3]
	v_mov_b32_e32 v15, v1
	v_lshl_add_u64 v[22:23], v[10:11], 0, v[14:15]
	global_load_dwordx4 v[190:193], v[22:23], off
	v_add_u32_e32 v16, 0, v14
	v_mad_u64_u32 v[18:19], s[0:1], v18, s56, v[16:17]
	v_add_u32_e32 v7, 0x200, v6
	s_movk_i32 s8, 0x240
	s_ashr_i32 s14, s7, 7
	v_mov_b32_e32 v222, v18
	global_load_dwordx4 v[194:197], v[22:23], off offset:1024
	v_mov_b32_e32 v223, v18
	v_ashrrev_i32_e32 v18, 4, v7
	v_ashrrev_i32_e32 v19, 31, v18
	v_lshl_add_u64 v[10:11], s[46:47], 0, v[18:19]
	v_mad_u64_u32 v[12:13], s[0:1], v10, s63, v[20:21]
	v_mov_b32_e32 v10, v13
	v_mad_u64_u32 v[10:11], s[0:1], v11, s63, v[10:11]
	v_mov_b32_e32 v13, v10
	v_lshl_add_u64 v[10:11], v[12:13], 0, s[2:3]
	v_lshl_add_u64 v[14:15], v[10:11], 0, v[14:15]
	global_load_dwordx4 v[198:201], v[14:15], off
	v_mad_u64_u32 v[16:17], s[0:1], v18, s56, v[16:17]
	v_ashrrev_i32_e32 v18, 5, v6
	v_ashrrev_i32_e32 v19, 31, v18
	s_lshl_b32 s2, s2, 1
	v_mov_b32_e32 v224, v16
	global_load_dwordx4 v[202:205], v[14:15], off offset:1024
	v_lshlrev_b32_e32 v14, 4, v96
	v_mov_b32_e32 v15, v1
	v_mov_b32_e32 v225, v16
	v_lshl_add_u64 v[10:11], s[46:47], 0, v[18:19]
	v_mad_u64_u32 v[12:13], s[0:1], v10, s63, v[20:21]
	v_mov_b32_e32 v10, v13
	v_mad_u64_u32 v[10:11], s[0:1], v11, s63, v[10:11]
	v_mov_b32_e32 v13, v10
	v_lshl_add_u64 v[10:11], v[12:13], 0, s[2:3]
	v_lshl_add_u64 v[10:11], v[10:11], 0, v[14:15]
	global_load_dwordx4 v[206:209], v[10:11], off offset:2048
	v_add_u32_e32 v16, 0, v14
	v_mad_u64_u32 v[18:19], s[0:1], v18, s8, v[16:17]
	v_mov_b32_e32 v226, v18
	v_ashrrev_i32_e32 v18, 5, v7
	v_ashrrev_i32_e32 v19, 31, v18
	v_lshl_add_u64 v[10:11], s[46:47], 0, v[18:19]
	v_mad_u64_u32 v[12:13], s[0:1], v10, s63, v[20:21]
	v_mov_b32_e32 v10, v13
	v_mad_u64_u32 v[10:11], s[0:1], v11, s63, v[10:11]
	v_mov_b32_e32 v13, v10
	v_lshl_add_u64 v[10:11], v[12:13], 0, s[2:3]
	v_lshl_add_u64 v[10:11], v[10:11], 0, v[14:15]
	global_load_dwordx4 v[210:213], v[10:11], off offset:2048
	v_mad_u64_u32 v[18:19], s[0:1], v18, s8, v[16:17]
	v_add_u32_e32 v7, 0x400, v6
	v_add_u32_e32 v6, 0x600, v6
	v_ashrrev_i32_e32 v6, 5, v6
	v_mov_b32_e32 v227, v18
	v_ashrrev_i32_e32 v18, 5, v7
	v_ashrrev_i32_e32 v19, 31, v18
	v_lshl_add_u64 v[10:11], s[46:47], 0, v[18:19]
	v_mad_u64_u32 v[12:13], s[0:1], v10, s63, v[20:21]
	v_mov_b32_e32 v10, v13
	v_mad_u64_u32 v[10:11], s[0:1], v11, s63, v[10:11]
	v_mov_b32_e32 v13, v10
	v_lshl_add_u64 v[10:11], v[12:13], 0, s[2:3]
	v_lshl_add_u64 v[10:11], v[10:11], 0, v[14:15]
	global_load_dwordx4 v[214:217], v[10:11], off offset:2048
	v_mad_u64_u32 v[18:19], s[0:1], v18, s8, v[16:17]
	v_ashrrev_i32_e32 v7, 31, v6
	v_mov_b32_e32 v228, v18
	v_lshl_add_u64 v[10:11], s[46:47], 0, v[6:7]
	v_mad_u64_u32 v[12:13], s[0:1], v10, s63, v[20:21]
	v_mov_b32_e32 v10, v13
	v_mad_u64_u32 v[10:11], s[0:1], v11, s63, v[10:11]
	v_mov_b32_e32 v13, v10
	v_lshl_add_u64 v[10:11], v[12:13], 0, s[2:3]
	v_lshl_add_u64 v[10:11], v[10:11], 0, v[14:15]
	global_load_dwordx4 v[218:221], v[10:11], off offset:2048
	v_mad_u64_u32 v[6:7], s[0:1], v6, s8, v[16:17]
	s_lshl_b32 s0, s76, 1
	s_and_b32 s15, s0, 2
	s_lshl_b32 s0, s14, 4
	v_lshl_or_b32 v17, s15, 4, v9
	v_mov_b32_e32 v229, v6
	s_waitcnt vmcnt(7)
	ds_write_b128 v222, v[190:193]
	s_waitcnt vmcnt(6)
	ds_write_b128 v223, v[194:197] offset:17408
	s_waitcnt vmcnt(5)
	ds_write_b128 v224, v[198:201]
	s_waitcnt vmcnt(4)
	ds_write_b128 v225, v[202:205] offset:17408
	s_waitcnt vmcnt(3)
	ds_write_b128 v226, v[206:209] offset:55296
	s_waitcnt vmcnt(2)
	ds_write_b128 v227, v[210:213] offset:55296
	s_waitcnt vmcnt(1)
	ds_write_b128 v228, v[214:217] offset:55296
	s_waitcnt vmcnt(0)
	ds_write_b128 v229, v[218:221] offset:55296
	v_lshrrev_b32_e32 v6, 2, v8
	v_and_or_b32 v12, v6, 12, s0
	v_or_b32_e32 v6, s0, v9
	v_mul_lo_u32 v6, v6, s56
	v_add_u32_e32 v7, 0, v6
	v_and_b32_e32 v10, 48, v8
	s_add_i32 s0, 0, 0x18d00
	v_add_u32_e32 v15, 0, v10
	v_lshl_add_u32 v13, v12, 2, s0
	v_mov_b32_e32 v6, 0
	s_cmp_gt_i32 s14, s15
	v_add_u32_e32 v14, v7, v10
	v_or_b32_e32 v10, 3, v12
	v_or_b32_e32 v11, 2, v12
	v_mov_b32_e32 v7, 0
	s_waitcnt lgkmcnt(0)
	s_barrier
	s_cbranch_scc1 .LBB0_889
	v_mad_u32_u24 v6, v17, s56, v15
	ds_read_b128 v[18:21], v14 offset:17408
	ds_read_b128 v[22:25], v6
	v_cmp_le_i32_e32 vcc, v12, v17
	s_waitcnt lgkmcnt(0)
	v_mfma_f32_16x16x32_bf16 v[18:21], v[18:21], v[22:25], 0
	ds_read_b128 v[22:25], v14 offset:17472
	ds_read_b128 v[26:29], v6 offset:64
	s_waitcnt lgkmcnt(0)
	v_mfma_f32_16x16x32_bf16 v[18:21], v[22:25], v[26:29], v[18:21]
	ds_read_b128 v[22:25], v14 offset:17536
	ds_read_b128 v[26:29], v6 offset:128
	s_waitcnt lgkmcnt(0)
	v_mfma_f32_16x16x32_bf16 v[18:21], v[22:25], v[26:29], v[18:21]
	ds_read_b128 v[22:25], v14 offset:17600
	ds_read_b128 v[26:29], v6 offset:192
	v_lshl_add_u32 v6, v17, 2, 0
	v_add_u32_e32 v6, 0x18c00, v6
	s_waitcnt lgkmcnt(0)
	v_mfma_f32_16x16x32_bf16 v[18:21], v[22:25], v[26:29], v[18:21]
	ds_read_b32 v7, v6
	ds_read_b128 v[22:25], v13
	s_waitcnt lgkmcnt(0)
	v_add_f32_e32 v6, v7, v22
	v_mul_f32_e32 v6, 0x3fb8aa3b, v6
	v_exp_f32_e32 v6, v6
	s_nop 1
	v_mul_f32_e32 v6, v18, v6
	v_cndmask_b32_e32 v16, 0, v6, vcc
	v_add_f32_e32 v6, v7, v23
	v_mul_f32_e32 v6, 0x3fb8aa3b, v6
	v_exp_f32_e32 v6, v6
	v_cmp_lt_i32_e32 vcc, v12, v17
	v_mul_f32_e32 v6, v19, v6
	s_nop 0
	v_cndmask_b32_e32 v22, 0, v6, vcc
	v_add_f32_e32 v6, v7, v24
	v_add_f32_e32 v7, v7, v25
	v_mul_f32_e32 v6, 0x3fb8aa3b, v6
	v_mul_f32_e32 v7, 0x3fb8aa3b, v7
	v_exp_f32_e32 v6, v6
	v_exp_f32_e32 v7, v7
	v_cmp_le_i32_e32 vcc, v11, v17
	v_pk_mul_f32 v[18:19], v[20:21], v[6:7]
	s_nop 0
	v_cvt_pk_bf16_f32 v7, v18, v19
	v_cvt_pk_bf16_f32 v6, v16, v22
	v_cndmask_b32_e32 v16, 0, v7, vcc
	v_cmp_le_i32_e32 vcc, v10, v17
	s_nop 1
	v_cndmask_b32_sdwa v7, v1, v7, vcc dst_sel:DWORD dst_unused:UNUSED_PAD src0_sel:DWORD src1_sel:WORD_1
	v_perm_b32 v7, v7, v16, s4
